# prep weight-transpose tiles: next tile's rows requested before the current tile goes through LDS (alternating register sets)
# baseline (speedup 1.0000x reference)
.LBB0_435:
	s_and_b64 vcc, exec, s[0:1]
	s_cbranch_vccz .LBB0_569
	s_mov_b32 s15, s45
	s_mov_b32 s14, 0
	s_add_i32 s26, s14, s76
	s_lshl_b64 s[0:1], s[14:15], 3
	s_add_u32 s0, s70, s0
	v_readlane_b32 s4, v253, 62
	s_addc_u32 s1, s71, s1
	v_readlane_b32 s6, v254, 0
	v_readlane_b32 s7, v254, 1
	s_add_u32 s2, s6, s14
	s_addc_u32 s3, s7, 0
	s_add_i32 s4, s14, s69
	s_add_i32 s36, s14, s72
	s_waitcnt vmcnt(0)
	v_mbcnt_lo_u32_b32 v36, -1, 0
	v_mbcnt_hi_u32_b32 v36, -1, v36
	s_mov_b32 s34, s4
	s_cmpk_gt_i32 s4, 0x163f
	v_lshl_add_u32 v176, s26, 6, v36
	v_readlane_b32 s5, v253, 63
	s_cbranch_scc1 .LBB0_488
	v_ashrrev_i32_e32 v2, 6, v176
	v_and_b32_e32 v3, 63, v36
	s_movk_i32 s4, 0x104
	v_mul_lo_u32 v0, v2, s4
	v_lshlrev_b32_e32 v1, 2, v3
	v_add3_u32 v4, 0, v0, v1
	v_lshlrev_b32_e32 v0, 3, v36
	s_waitcnt vmcnt(3)
	v_ashrrev_i32_e32 v18, 3, v176
	v_and_b32_e32 v0, 56, v0
	v_mul_u32_u24_e32 v1, 0x104, v0
	v_lshlrev_b32_e32 v19, 2, v18
	v_add_u32_e32 v5, 0x820, v4
	v_add_u32_e32 v6, 16, v2
	v_add_u32_e32 v7, 0x1040, v4
	v_add_u32_e32 v8, 24, v2
	v_add_u32_e32 v9, 0x1860, v4
	v_add_u32_e32 v10, 32, v2
	v_add_u32_e32 v11, 0x2080, v4
	v_add_u32_e32 v12, 40, v2
	v_add_u32_e32 v13, 0x28a0, v4
	v_add_u32_e32 v14, 48, v2
	v_add_u32_e32 v15, 0x30c0, v4
	v_add_u32_e32 v16, 56, v2
	v_add_u32_e32 v17, 0x38e0, v4
	v_add3_u32 v19, 0, v1, v19
	v_lshlrev_b32_e32 v192, 1, v0
	s_mov_b32 s15, s34
	s_mov_b32 s101, 0
	s_mov_b32 s98, 0
	s_mov_b32 s100, s36
	s_cmpk_lg_i32 s36, 0x100
	s_cbranch_scc1 .LBB0_439
	s_movk_i32 s100, 0xc0
	s_addk_i32 s15, 0xffc0
	s_cmp_lt_i32 s15, 0
	s_cbranch_scc1 .LBB0_488
	s_branch .LBB0_439

.LBB0_470:
	v_or_b32_e32 v0, s21, v3
	s_cmp_lt_i32 s28, 0
	v_cmp_le_i32_e32 vcc, s23, v0
	s_cselect_b64 s[4:5], -1, 0
	s_waitcnt lgkmcnt(0)
	v_add_u32_e32 v1, s28, v3
	v_add_u32_e32 v0, s24, v0
	s_mul_i32 s27, s27, s25
	v_cndmask_b32_e64 v0, v1, v0, s[4:5]
	s_sub_i32 s12, s22, s27
	v_ashrrev_i32_e32 v1, 31, v0
	s_lshl_b32 s12, s12, 6
	v_lshl_add_u64 v[0:1], v[0:1], 2, s[10:11]
	s_add_u32 s4, s2, s6
	s_addc_u32 s5, s3, s7
	v_add_u32_e32 v148, s21, v18
	v_ashrrev_i32_e32 v151, 31, v148
	v_mad_u64_u32 v[148:149], s[18:19], v148, s20, 0
	v_mov_b32_e32 v150, v149
	v_mad_u64_u32 v[150:151], s[18:19], v151, s20, v[150:151]
	v_mov_b32_e32 v149, v150
	v_lshl_add_u64 v[148:149], v[148:149], 1, s[4:5]
	s_ashr_i32 s13, s12, 31
	v_lshl_add_u64 v[148:149], s[12:13], 1, v[148:149]
	v_lshl_add_u64 v[144:145], v[148:149], 0, v[192:193]
	s_waitcnt vmcnt(0)
	s_cmp_eq_u32 s98, 0
	s_cbranch_scc0 .Lcvt_issB
	v_mov_b32_e32 v128, 0
	v_mov_b32_e32 v129, 0
	v_mov_b32_e32 v130, 0
	v_mov_b32_e32 v131, 0
	v_mov_b32_e32 v132, 0
	v_mov_b32_e32 v133, 0
	v_mov_b32_e32 v134, 0
	v_mov_b32_e32 v135, 0
	s_mov_b64 s[18:19], exec
	s_andn2_b64 exec, exec, vcc
	s_cbranch_execz .Lcvt_joinA
	v_add_u32_e32 v80, s12, v2
	v_ashrrev_i32_e32 v81, 31, v80
	v_mul_lo_u32 v81, s8, v81
	v_mul_lo_u32 v84, s9, v80
	v_mad_u64_u32 v[82:83], s[4:5], s8, v80, 0
	v_add3_u32 v83, v83, v81, v84
	v_lshl_add_u64 v[82:83], v[82:83], 2, v[0:1]
	global_load_dword v128, v[82:83], off
	v_add_u32_e32 v86, 8, v80
	v_ashrrev_i32_e32 v87, 31, v86
	v_mul_lo_u32 v87, s8, v87
	v_mul_lo_u32 v90, s9, v86
	v_mad_u64_u32 v[88:89], s[4:5], s8, v86, 0
	v_add3_u32 v89, v89, v87, v90
	v_lshl_add_u64 v[88:89], v[88:89], 2, v[0:1]
	global_load_dword v129, v[88:89], off
	v_add_u32_e32 v92, s12, v6
	v_ashrrev_i32_e32 v93, 31, v92
	v_mul_lo_u32 v93, s8, v93
	v_mul_lo_u32 v96, s9, v92
	v_mad_u64_u32 v[94:95], s[4:5], s8, v92, 0
	v_add3_u32 v95, v95, v93, v96
	v_lshl_add_u64 v[94:95], v[94:95], 2, v[0:1]
	global_load_dword v130, v[94:95], off
	v_add_u32_e32 v98, s12, v8
	v_ashrrev_i32_e32 v99, 31, v98
	v_mul_lo_u32 v99, s8, v99
	v_mul_lo_u32 v102, s9, v98
	v_mad_u64_u32 v[100:101], s[4:5], s8, v98, 0
	v_add3_u32 v101, v101, v99, v102
	v_lshl_add_u64 v[100:101], v[100:101], 2, v[0:1]
	global_load_dword v131, v[100:101], off
	v_add_u32_e32 v104, s12, v10
	v_ashrrev_i32_e32 v105, 31, v104
	v_mul_lo_u32 v105, s8, v105
	v_mul_lo_u32 v108, s9, v104
	v_mad_u64_u32 v[106:107], s[4:5], s8, v104, 0
	v_add3_u32 v107, v107, v105, v108
	v_lshl_add_u64 v[106:107], v[106:107], 2, v[0:1]
	global_load_dword v132, v[106:107], off
	v_add_u32_e32 v110, s12, v12
	v_ashrrev_i32_e32 v111, 31, v110
	v_mul_lo_u32 v111, s8, v111
	v_mul_lo_u32 v114, s9, v110
	v_mad_u64_u32 v[112:113], s[4:5], s8, v110, 0
	v_add3_u32 v113, v113, v111, v114
	v_lshl_add_u64 v[112:113], v[112:113], 2, v[0:1]
	global_load_dword v133, v[112:113], off
	v_add_u32_e32 v116, s12, v14
	v_ashrrev_i32_e32 v117, 31, v116
	v_mul_lo_u32 v117, s8, v117
	v_mul_lo_u32 v120, s9, v116
	v_mad_u64_u32 v[118:119], s[4:5], s8, v116, 0
	v_add3_u32 v119, v119, v117, v120
	v_lshl_add_u64 v[118:119], v[118:119], 2, v[0:1]
	global_load_dword v134, v[118:119], off
	v_add_u32_e32 v122, s12, v16
	v_ashrrev_i32_e32 v123, 31, v122
	v_mul_lo_u32 v123, s8, v123
	v_mul_lo_u32 v126, s9, v122
	v_mad_u64_u32 v[124:125], s[4:5], s8, v122, 0
	v_add3_u32 v125, v125, v123, v126
	v_lshl_add_u64 v[124:125], v[124:125], 2, v[0:1]
	global_load_dword v135, v[124:125], off
.Lcvt_joinA:
	s_mov_b64 exec, s[18:19]
	s_branch .Lcvt_issued
.Lcvt_issB:
	v_mov_b32_e32 v136, 0
	v_mov_b32_e32 v137, 0
	v_mov_b32_e32 v138, 0
	v_mov_b32_e32 v139, 0
	v_mov_b32_e32 v140, 0
	v_mov_b32_e32 v141, 0
	v_mov_b32_e32 v142, 0
	v_mov_b32_e32 v143, 0
	s_mov_b64 s[18:19], exec
	s_andn2_b64 exec, exec, vcc
	s_cbranch_execz .Lcvt_joinB
	v_add_u32_e32 v80, s12, v2
	v_ashrrev_i32_e32 v81, 31, v80
	v_mul_lo_u32 v81, s8, v81
	v_mul_lo_u32 v84, s9, v80
	v_mad_u64_u32 v[82:83], s[4:5], s8, v80, 0
	v_add3_u32 v83, v83, v81, v84
	v_lshl_add_u64 v[82:83], v[82:83], 2, v[0:1]
	global_load_dword v136, v[82:83], off
	v_add_u32_e32 v86, 8, v80
	v_ashrrev_i32_e32 v87, 31, v86
	v_mul_lo_u32 v87, s8, v87
	v_mul_lo_u32 v90, s9, v86
	v_mad_u64_u32 v[88:89], s[4:5], s8, v86, 0
	v_add3_u32 v89, v89, v87, v90
	v_lshl_add_u64 v[88:89], v[88:89], 2, v[0:1]
	global_load_dword v137, v[88:89], off
	v_add_u32_e32 v92, s12, v6
	v_ashrrev_i32_e32 v93, 31, v92
	v_mul_lo_u32 v93, s8, v93
	v_mul_lo_u32 v96, s9, v92
	v_mad_u64_u32 v[94:95], s[4:5], s8, v92, 0
	v_add3_u32 v95, v95, v93, v96
	v_lshl_add_u64 v[94:95], v[94:95], 2, v[0:1]
	global_load_dword v138, v[94:95], off
	v_add_u32_e32 v98, s12, v8
	v_ashrrev_i32_e32 v99, 31, v98
	v_mul_lo_u32 v99, s8, v99
	v_mul_lo_u32 v102, s9, v98
	v_mad_u64_u32 v[100:101], s[4:5], s8, v98, 0
	v_add3_u32 v101, v101, v99, v102
	v_lshl_add_u64 v[100:101], v[100:101], 2, v[0:1]
	global_load_dword v139, v[100:101], off
	v_add_u32_e32 v104, s12, v10
	v_ashrrev_i32_e32 v105, 31, v104
	v_mul_lo_u32 v105, s8, v105
	v_mul_lo_u32 v108, s9, v104
	v_mad_u64_u32 v[106:107], s[4:5], s8, v104, 0
	v_add3_u32 v107, v107, v105, v108
	v_lshl_add_u64 v[106:107], v[106:107], 2, v[0:1]
	global_load_dword v140, v[106:107], off
	v_add_u32_e32 v110, s12, v12
	v_ashrrev_i32_e32 v111, 31, v110
	v_mul_lo_u32 v111, s8, v111
	v_mul_lo_u32 v114, s9, v110
	v_mad_u64_u32 v[112:113], s[4:5], s8, v110, 0
	v_add3_u32 v113, v113, v111, v114
	v_lshl_add_u64 v[112:113], v[112:113], 2, v[0:1]
	global_load_dword v141, v[112:113], off
	v_add_u32_e32 v116, s12, v14
	v_ashrrev_i32_e32 v117, 31, v116
	v_mul_lo_u32 v117, s8, v117
	v_mul_lo_u32 v120, s9, v116
	v_mad_u64_u32 v[118:119], s[4:5], s8, v116, 0
	v_add3_u32 v119, v119, v117, v120
	v_lshl_add_u64 v[118:119], v[118:119], 2, v[0:1]
	global_load_dword v142, v[118:119], off
	v_add_u32_e32 v122, s12, v16
	v_ashrrev_i32_e32 v123, 31, v122
	v_mul_lo_u32 v123, s8, v123
	v_mul_lo_u32 v126, s9, v122
	v_mad_u64_u32 v[124:125], s[4:5], s8, v122, 0
	v_add3_u32 v125, v125, v123, v126
	v_lshl_add_u64 v[124:125], v[124:125], 2, v[0:1]
	global_load_dword v143, v[124:125], off

.Lcvt_issued:
	s_cmp_eq_u32 s101, 0
	s_cbranch_scc1 .Lcvt_first
	s_barrier
	s_cmp_eq_u32 s98, 0
	s_cbranch_scc1 .Lcvt_wB1
	ds_write_b32 v4, v128
	ds_write_b32 v5, v129
	ds_write_b32 v7, v130
	ds_write_b32 v9, v131
	ds_write_b32 v11, v132
	ds_write_b32 v13, v133
	ds_write_b32 v15, v134
	ds_write_b32 v17, v135
	s_branch .Lcvt_wdone1
.Lcvt_wB1:
	ds_write_b32 v4, v136
	ds_write_b32 v5, v137
	ds_write_b32 v7, v138
	ds_write_b32 v9, v139
	ds_write_b32 v11, v140
	ds_write_b32 v13, v141
	ds_write_b32 v15, v142
	ds_write_b32 v17, v143
.Lcvt_wdone1:
	s_waitcnt lgkmcnt(0)
	s_barrier
	ds_read2_b32 v[0:1], v19 offset1:65
	ds_read2_b32 v[22:23], v19 offset0:130 offset1:195
	v_add_u32_e32 v20, 0x400, v19
	ds_read2_b32 v[24:25], v20 offset0:4 offset1:69
	ds_read2_b32 v[26:27], v20 offset0:134 offset1:199
	s_waitcnt lgkmcnt(3)
	v_cvt_pk_bf16_f32 v20, v0, v1
	s_waitcnt lgkmcnt(2)
	v_cvt_pk_bf16_f32 v21, v22, v23
	s_waitcnt lgkmcnt(1)
	v_cvt_pk_bf16_f32 v22, v24, v25
	s_waitcnt lgkmcnt(0)
	v_cvt_pk_bf16_f32 v23, v26, v27
	global_store_dwordx4 v[146:147], v[20:23], off
.Lcvt_first:
	s_mov_b32 s101, 1
	v_mov_b32_e32 v146, v144
	v_mov_b32_e32 v147, v145
	s_xor_b32 s98, s98, 1
	s_add_i32 s15, s15, s100
	s_cmpk_gt_i32 s15, 0x163f
	s_cbranch_scc0 .LBB0_439
	s_waitcnt vmcnt(0)
	s_barrier
	s_cmp_eq_u32 s98, 0
	s_cbranch_scc1 .Lcvt_wB2
	ds_write_b32 v4, v128
	ds_write_b32 v5, v129
	ds_write_b32 v7, v130
	ds_write_b32 v9, v131
	ds_write_b32 v11, v132
	ds_write_b32 v13, v133
	ds_write_b32 v15, v134
	ds_write_b32 v17, v135
	s_branch .Lcvt_wdone2

.Lcvt_wdone2:
	s_waitcnt lgkmcnt(0)
	s_barrier
	ds_read2_b32 v[0:1], v19 offset1:65
	ds_read2_b32 v[22:23], v19 offset0:130 offset1:195
	v_add_u32_e32 v20, 0x400, v19
	ds_read2_b32 v[24:25], v20 offset0:4 offset1:69
	ds_read2_b32 v[26:27], v20 offset0:134 offset1:199
	s_waitcnt lgkmcnt(3)
	v_cvt_pk_bf16_f32 v20, v0, v1
	s_waitcnt lgkmcnt(2)
	v_cvt_pk_bf16_f32 v21, v22, v23
	s_waitcnt lgkmcnt(1)
	v_cvt_pk_bf16_f32 v22, v24, v25
	s_waitcnt lgkmcnt(0)
	v_cvt_pk_bf16_f32 v23, v26, v27
	global_store_dwordx4 v[146:147], v[20:23], off
	s_branch .LBB0_488
	s_nop 0
	s_nop 0
